# back-edge rotation: loop-carried pointer updates and exit test of the four GEMM K-loops moved in front of the loop-back barrier
# speedup vs baseline: 1.0007x; 1.0007x over previous
; #define PG8_STAGE(bufoff, gbase, voff) do { _Pragma("unroll") for (int _i = 0; _i < 2; ++_i) \
;         __builtin_amdgcn_global_load_lds((const unsigned*)((const char*)(gbase) + (voff)[_i]), (LAS unsigned*)(lds + (bufoff) + ldsw + _i * 8192), 16, 0, 0); } while (0)
; #define PG8_LDA(dst, b, h) do { _Pragma("unroll") for (int m = 0; m < 4; ++m) _Pragma("unroll") for (int k = 0; k < 2; ++k) dst[m][k] = *(const LAS bf16x8*)(lds + PG8_SA(b, h) + aoff + m * 2048 + k * 1024); } while (0)
; #define PG8_LDB(dst, b, h) do { _Pragma("unroll") for (int n = 0; n < 2; ++n) _Pragma("unroll") for (int k = 0; k < 2; ++k) dst[n][k] = *(const LAS bf16x8*)(lds + PG8_SB(b, h) + boff + n * 2048 + k * 1024); } while (0)
; #define PG8_MMA(ai, bj, At, Bt) do { __builtin_amdgcn_s_setprio(1); _Pragma("unroll") for (int m = 0; m < 4; ++m) _Pragma("unroll") for (int n = 0; n < 2; ++n) _Pragma("unroll") for (int k = 0; k < 2; ++k) \
;         acc[ai][bj][m][n] = __builtin_amdgcn_mfma_f32_16x16x32_bf16(Bt[n][k], At[m][k], acc[ai][bj][m][n], 0, 0, 0); __builtin_amdgcn_s_setprio(0); } while (0)
; #define PG8_WAIT_V(n) asm volatile("s_waitcnt vmcnt(" #n ")" ::: "memory")
; #define PG8_WAIT_L(n) asm volatile("s_waitcnt lgkmcnt(" #n ")" ::: "memory")
; #define PG8_BAR __builtin_amdgcn_s_barrier()
; #define PG8_SCHED __builtin_amdgcn_sched_barrier(0)
; template <class Epi, int AC0, int BC0, int NT0, int AC1, int BC1, int NT1>
; __device__ __forceinline__ void gemm_phase(LAS unsigned char* lds, const Gemm g, const StaticOrder& S, const Epi& E, int tid) {
;     ...
;             PG8_LDB(B0, 1, 0); PG8_LDB(B1, 1, 1); PG8_SCHED; PG8_LDA(At, 1, 0); PG8_STAGE(PG8_SA(0, 1), a2 + hstepA, voffA);
;             PG8_WAIT_V(8); PG8_WAIT_L(0); PG8_BAR; PG8_MMA(0, 0, At, B0); PG8_MMA(0, 1, At, B1); PG8_BAR; PG8_SCHED;
.Lmid_P1:
	s_add_i32 s29, 0, 0x18000
	s_add_i32 s33, 0, 0x1c000
	v_add_u32_e32 v70, s29, v188
	v_add_u32_e32 v158, s33, v188
	ds_read_b128 v[50:53], v70
	ds_read_b128 v[54:57], v70 offset:1024
	ds_read_b128 v[66:69], v70 offset:2048
	ds_read_b128 v[70:73], v70 offset:3072
	ds_read_b128 v[146:149], v158
	ds_read_b128 v[150:153], v158 offset:1024
	ds_read_b128 v[154:157], v158 offset:2048
	ds_read_b128 v[158:161], v158 offset:3072
	s_add_u32 s12, s12, 0x40000
	s_addc_u32 s13, s13, 0
	s_mov_b32 m0, s97
	v_lshl_add_u64 v[238:239], s[12:13], 0, v[164:165]
	ds_read_b128 v[198:201], v194 offset:32768
	ds_read_b128 v[202:205], v194 offset:33792
	ds_read_b128 v[206:209], v194 offset:34816
	ds_read_b128 v[210:213], v194 offset:35840
	ds_read_b128 v[214:217], v194 offset:36864
	ds_read_b128 v[218:221], v194 offset:37888
	ds_read_b128 v[226:229], v194 offset:38912
	ds_read_b128 v[230:233], v194 offset:39936
	global_load_lds_dwordx4 v[238:239], off
	v_lshl_add_u64 v[238:239], s[12:13], 0, v[168:169]
	s_mov_b32 m0, s93
	s_nop 0
	global_load_lds_dwordx4 v[238:239], off
	s_waitcnt vmcnt(8)
	s_waitcnt lgkmcnt(0)
	s_barrier
	s_setprio 1
	s_waitcnt lgkmcnt(0)
	v_mfma_f32_16x16x32_bf16 v[142:145], v[50:53], v[198:201], v[142:145]
	v_mfma_f32_16x16x32_bf16 v[138:141], v[66:69], v[198:201], v[138:141]
	v_mfma_f32_16x16x32_bf16 v[126:129], v[50:53], v[206:209], v[126:129]
	v_mfma_f32_16x16x32_bf16 v[122:125], v[66:69], v[206:209], v[122:125]
	v_mfma_f32_16x16x32_bf16 v[110:113], v[50:53], v[214:217], v[110:113]
	v_mfma_f32_16x16x32_bf16 v[106:109], v[66:69], v[214:217], v[106:109]
	v_mfma_f32_16x16x32_bf16 v[94:97], v[50:53], v[226:229], v[94:97]
	v_mfma_f32_16x16x32_bf16 v[90:93], v[66:69], v[226:229], v[90:93]
	v_mfma_f32_16x16x32_bf16 v[142:145], v[54:57], v[202:205], v[142:145]
	v_mfma_f32_16x16x32_bf16 v[138:141], v[70:73], v[202:205], v[138:141]
	v_mfma_f32_16x16x32_bf16 v[126:129], v[54:57], v[210:213], v[126:129]
	v_mfma_f32_16x16x32_bf16 v[122:125], v[70:73], v[210:213], v[122:125]
	v_mfma_f32_16x16x32_bf16 v[110:113], v[54:57], v[218:221], v[110:113]
	v_mfma_f32_16x16x32_bf16 v[106:109], v[70:73], v[218:221], v[106:109]
	v_mfma_f32_16x16x32_bf16 v[94:97], v[54:57], v[230:233], v[94:97]
	v_mfma_f32_16x16x32_bf16 v[90:93], v[70:73], v[230:233], v[90:93]
	s_setprio 0
	s_setprio 1
	v_mfma_f32_16x16x32_bf16 v[134:137], v[146:149], v[198:201], v[134:137]
	v_mfma_f32_16x16x32_bf16 v[130:133], v[154:157], v[198:201], v[130:133]
	v_mfma_f32_16x16x32_bf16 v[118:121], v[146:149], v[206:209], v[118:121]
	v_mfma_f32_16x16x32_bf16 v[114:117], v[154:157], v[206:209], v[114:117]
	v_mfma_f32_16x16x32_bf16 v[102:105], v[146:149], v[214:217], v[102:105]
	v_mfma_f32_16x16x32_bf16 v[98:101], v[154:157], v[214:217], v[98:101]
	v_mfma_f32_16x16x32_bf16 v[86:89], v[146:149], v[226:229], v[86:89]
	v_mfma_f32_16x16x32_bf16 v[82:85], v[154:157], v[226:229], v[82:85]
	v_mfma_f32_16x16x32_bf16 v[134:137], v[150:153], v[202:205], v[134:137]
	v_mfma_f32_16x16x32_bf16 v[130:133], v[158:161], v[202:205], v[130:133]
	v_mfma_f32_16x16x32_bf16 v[118:121], v[150:153], v[210:213], v[118:121]
	v_mfma_f32_16x16x32_bf16 v[114:117], v[158:161], v[210:213], v[114:117]
	v_mfma_f32_16x16x32_bf16 v[102:105], v[150:153], v[218:221], v[102:105]
	v_mfma_f32_16x16x32_bf16 v[98:101], v[158:161], v[218:221], v[98:101]
	v_mfma_f32_16x16x32_bf16 v[86:89], v[150:153], v[230:233], v[86:89]
	v_mfma_f32_16x16x32_bf16 v[82:85], v[158:161], v[230:233], v[82:85]
	s_setprio 0
	s_barrier
; #define PG8_STAGE(bufoff, gbase, voff) do { _Pragma("unroll") for (int _i = 0; _i < 2; ++_i) \
;         __builtin_amdgcn_global_load_lds((const unsigned*)((const char*)(gbase) + (voff)[_i]), (LAS unsigned*)(lds + (bufoff) + ldsw + _i * 8192), 16, 0, 0); } while (0)
; #define PG8_LDA(dst, b, h) do { _Pragma("unroll") for (int m = 0; m < 4; ++m) _Pragma("unroll") for (int k = 0; k < 2; ++k) dst[m][k] = *(const LAS bf16x8*)(lds + PG8_SA(b, h) + aoff + m * 2048 + k * 1024); } while (0)
; #define PG8_MMA(ai, bj, At, Bt) do { __builtin_amdgcn_s_setprio(1); _Pragma("unroll") for (int m = 0; m < 4; ++m) _Pragma("unroll") for (int n = 0; n < 2; ++n) _Pragma("unroll") for (int k = 0; k < 2; ++k) \
;         acc[ai][bj][m][n] = __builtin_amdgcn_mfma_f32_16x16x32_bf16(Bt[n][k], At[m][k], acc[ai][bj][m][n], 0, 0, 0); __builtin_amdgcn_s_setprio(0); } while (0)
; #define PG8_WAIT_V(n) asm volatile("s_waitcnt vmcnt(" #n ")" ::: "memory")
; #define PG8_WAIT_L(n) asm volatile("s_waitcnt lgkmcnt(" #n ")" ::: "memory")
; #define PG8_BAR __builtin_amdgcn_s_barrier()
; #define PG8_SCHED __builtin_amdgcn_sched_barrier(0)
; template <class Epi, int AC0, int BC0, int NT0, int AC1, int BC1, int NT1>
; __device__ __forceinline__ void gemm_phase(LAS unsigned char* lds, const Gemm g, const StaticOrder& S, const Epi& E, int tid) {
;     ...
;         for (int t = 0; t < nt; t += 2) {
;             const bool last = (t == nt - 2);
;             const char* a1 = cA + (size_t)(t + 1) * kstep;
;             const char* a2 = last ? nA : cA + (size_t)(t + 2) * kstep; const char* b2 = last ? nB : cB + (size_t)(t + 2) * kstep;
;     ...
;             PG8_LDA(At, 1, 1); PG8_STAGE(PG8_SB(1, 0), b3, voffB); PG8_STAGE(PG8_SB(1, 1), b3 + hstepB, voffB); PG8_STAGE(PG8_SA(1, 0), a3, voffA);
;             PG8_WAIT_V(8); PG8_WAIT_L(0); PG8_BAR; PG8_MMA(1, 0, At, B0); PG8_MMA(1, 1, At, B1); PG8_BAR; PG8_SCHED;
;         }
	s_add_i32 s12, s29, s47
	v_lshl_add_u64 v[186:187], v[186:187], 0, s[20:21]
	s_mov_b32 m0, s12
	ds_read_b128 v[198:201], v194 offset:49152
	ds_read_b128 v[202:205], v194 offset:50176
	ds_read_b128 v[206:209], v194 offset:51200
	ds_read_b128 v[210:213], v194 offset:52224
	ds_read_b128 v[214:217], v194 offset:53248
	ds_read_b128 v[218:221], v194 offset:54272
	ds_read_b128 v[226:229], v194 offset:55296
	ds_read_b128 v[230:233], v194 offset:56320
	global_load_lds_dwordx4 v[186:187], off
	s_add_i32 m0, s12, 0x2000
	s_add_u32 s6, s6, 0x40080
	v_lshl_add_u64 v[186:187], v[222:223], 0, s[20:21]
	s_addc_u32 s7, s7, 0
	s_add_i32 s12, s33, s47
	global_load_lds_dwordx4 v[186:187], off
	v_lshl_add_u64 v[186:187], s[6:7], 0, v[166:167]
	s_mov_b32 m0, s12
	s_nop 0
	global_load_lds_dwordx4 v[186:187], off
	v_lshl_add_u64 v[186:187], s[6:7], 0, v[170:171]
	s_add_i32 m0, s12, 0x2000
	s_nop 0
	global_load_lds_dwordx4 v[186:187], off
	v_lshl_add_u64 v[186:187], v[234:235], 0, s[20:21]
	s_mov_b32 m0, s19
	s_nop 0
	global_load_lds_dwordx4 v[186:187], off
	v_lshl_add_u64 v[186:187], v[236:237], 0, s[20:21]
	s_mov_b32 m0, s46
	s_nop 0
	global_load_lds_dwordx4 v[186:187], off
	s_waitcnt vmcnt(8)
	s_waitcnt lgkmcnt(0)
	s_barrier
	s_setprio 1
	s_waitcnt lgkmcnt(0)
	v_mfma_f32_16x16x32_bf16 v[78:81], v[50:53], v[198:201], v[78:81]
	v_mfma_f32_16x16x32_bf16 v[74:77], v[66:69], v[198:201], v[74:77]
	v_mfma_f32_16x16x32_bf16 v[62:65], v[50:53], v[206:209], v[62:65]
	v_mfma_f32_16x16x32_bf16 v[58:61], v[66:69], v[206:209], v[58:61]
	v_mfma_f32_16x16x32_bf16 v[38:41], v[50:53], v[214:217], v[38:41]
	v_mfma_f32_16x16x32_bf16 v[34:37], v[66:69], v[214:217], v[34:37]
	v_mfma_f32_16x16x32_bf16 v[14:17], v[50:53], v[226:229], v[14:17]
	v_mfma_f32_16x16x32_bf16 v[10:13], v[66:69], v[226:229], v[10:13]
	v_mfma_f32_16x16x32_bf16 v[78:81], v[54:57], v[202:205], v[78:81]
	v_mfma_f32_16x16x32_bf16 v[74:77], v[70:73], v[202:205], v[74:77]
	v_mfma_f32_16x16x32_bf16 v[62:65], v[54:57], v[210:213], v[62:65]
	v_mfma_f32_16x16x32_bf16 v[58:61], v[70:73], v[210:213], v[58:61]
	v_mfma_f32_16x16x32_bf16 v[38:41], v[54:57], v[218:221], v[38:41]
	v_mfma_f32_16x16x32_bf16 v[34:37], v[70:73], v[218:221], v[34:37]
	v_mfma_f32_16x16x32_bf16 v[14:17], v[54:57], v[230:233], v[14:17]
	v_mfma_f32_16x16x32_bf16 v[10:13], v[70:73], v[230:233], v[10:13]
	s_setprio 0
	s_setprio 1
	v_mfma_f32_16x16x32_bf16 v[26:29], v[146:149], v[198:201], v[26:29]
	v_mfma_f32_16x16x32_bf16 v[70:73], v[150:153], v[202:205], v[26:29]
	v_mfma_f32_16x16x32_bf16 v[26:29], v[154:157], v[198:201], v[30:33]
	v_mfma_f32_16x16x32_bf16 v[66:69], v[158:161], v[202:205], v[26:29]
	v_mfma_f32_16x16x32_bf16 v[26:29], v[146:149], v[206:209], v[42:45]
	v_mfma_f32_16x16x32_bf16 v[54:57], v[150:153], v[210:213], v[26:29]
	v_mfma_f32_16x16x32_bf16 v[26:29], v[154:157], v[206:209], v[46:49]
	v_mfma_f32_16x16x32_bf16 v[22:25], v[146:149], v[214:217], v[22:25]
	v_mfma_f32_16x16x32_bf16 v[18:21], v[154:157], v[214:217], v[18:21]
	v_mfma_f32_16x16x32_bf16 v[6:9], v[146:149], v[226:229], v[6:9]
	v_mfma_f32_16x16x32_bf16 v[2:5], v[154:157], v[226:229], v[2:5]
	v_mfma_f32_16x16x32_bf16 v[50:53], v[158:161], v[210:213], v[26:29]
	v_mfma_f32_16x16x32_bf16 v[22:25], v[150:153], v[218:221], v[22:25]
	v_mfma_f32_16x16x32_bf16 v[18:21], v[158:161], v[218:221], v[18:21]
	v_mfma_f32_16x16x32_bf16 v[6:9], v[150:153], v[230:233], v[6:9]
	v_mfma_f32_16x16x32_bf16 v[2:5], v[158:161], v[230:233], v[2:5]
	s_add_i32 s27, s27, 2
	s_add_u32 s0, s0, 0x100
	s_addc_u32 s1, s1, 0
	s_add_u32 s16, s16, 0x100
	s_addc_u32 s22, s22, 0
	s_cmp_gt_u32 s27, 13
	s_setprio 0
	s_barrier
	s_cbranch_scc0 .LBB0_124
	v_readlane_b32 s0, v254, 21
	v_readlane_b32 s1, v254, 22
	s_and_b64 vcc, exec, s[0:1]
	s_cbranch_vccz .LBB0_127
	s_barrier

; #define PG8_STAGE(bufoff, gbase, voff) do { _Pragma("unroll") for (int _i = 0; _i < 2; ++_i) \
;         __builtin_amdgcn_global_load_lds((const unsigned*)((const char*)(gbase) + (voff)[_i]), (LAS unsigned*)(lds + (bufoff) + ldsw + _i * 8192), 16, 0, 0); } while (0)
; #define PG8_LDA(dst, b, h) do { _Pragma("unroll") for (int m = 0; m < 4; ++m) _Pragma("unroll") for (int k = 0; k < 2; ++k) dst[m][k] = *(const LAS bf16x8*)(lds + PG8_SA(b, h) + aoff + m * 2048 + k * 1024); } while (0)
; #define PG8_LDB(dst, b, h) do { _Pragma("unroll") for (int n = 0; n < 2; ++n) _Pragma("unroll") for (int k = 0; k < 2; ++k) dst[n][k] = *(const LAS bf16x8*)(lds + PG8_SB(b, h) + boff + n * 2048 + k * 1024); } while (0)
; #define PG8_MMA(ai, bj, At, Bt) do { __builtin_amdgcn_s_setprio(1); _Pragma("unroll") for (int m = 0; m < 4; ++m) _Pragma("unroll") for (int n = 0; n < 2; ++n) _Pragma("unroll") for (int k = 0; k < 2; ++k) \
;         acc[ai][bj][m][n] = __builtin_amdgcn_mfma_f32_16x16x32_bf16(Bt[n][k], At[m][k], acc[ai][bj][m][n], 0, 0, 0); __builtin_amdgcn_s_setprio(0); } while (0)
; #define PG8_WAIT_V(n) asm volatile("s_waitcnt vmcnt(" #n ")" ::: "memory")
; #define PG8_WAIT_L(n) asm volatile("s_waitcnt lgkmcnt(" #n ")" ::: "memory")
; #define PG8_BAR __builtin_amdgcn_s_barrier()
; #define PG8_SCHED __builtin_amdgcn_sched_barrier(0)
; template <class Epi, int AC0, int BC0, int NT0, int AC1, int BC1, int NT1>
; __device__ __forceinline__ void gemm_phase(LAS unsigned char* lds, const Gemm g, const StaticOrder& S, const Epi& E, int tid) {
;     ...
;             const bool last = (t == nt - 2);
;             const char* a1 = cA + (size_t)(t + 1) * kstep;
;             const char* a2 = last ? nA : cA + (size_t)(t + 2) * kstep; const char* b2 = last ? nB : cB + (size_t)(t + 2) * kstep;
;             const char* a3 = a2 + kstep; const char* b3 = b2 + kstep;
;             PG8_LDB(B0, 0, 0); PG8_LDB(B1, 0, 1); PG8_SCHED; PG8_LDA(At, 0, 0); PG8_STAGE(PG8_SA(1, 1), a1 + hstepA, voffA);
;             PG8_WAIT_V(8); PG8_WAIT_L(0); PG8_BAR; PG8_MMA(0, 0, At, B0); PG8_MMA(0, 1, At, B1); PG8_BAR; PG8_SCHED;
;             PG8_LDA(At, 0, 1); PG8_STAGE(PG8_SB(0, 0), b2, voffB); PG8_STAGE(PG8_SB(0, 1), b2 + hstepB, voffB); PG8_STAGE(PG8_SA(0, 0), a2, voffA);
;             PG8_WAIT_V(8); PG8_WAIT_L(0); PG8_BAR; PG8_MMA(1, 0, At, B0); PG8_MMA(1, 1, At, B1); PG8_BAR; PG8_SCHED;
.LBB0_725:
	v_add_u32_e32 v142, s29, v222
	v_add_u32_e32 v158, s30, v222
	ds_read_b128 v[130:133], v142
	ds_read_b128 v[134:137], v142 offset:1024
	ds_read_b128 v[138:141], v142 offset:2048
	ds_read_b128 v[142:145], v142 offset:3072
	ds_read_b128 v[146:149], v158
	ds_read_b128 v[150:153], v158 offset:1024
	ds_read_b128 v[154:157], v158 offset:2048
	ds_read_b128 v[158:161], v158 offset:3072
	s_add_u32 s0, s14, 0x100
	s_addc_u32 s1, s15, 0
	s_cmp_eq_u32 s42, 4
	s_cselect_b32 vcc_hi, s19, s1
	s_cselect_b32 vcc_lo, s18, s0
	s_cselect_b32 s17, s3, s37
	s_cselect_b32 s16, s13, s33
	v_lshl_add_u64 v[212:213], s[14:15], 0, v[206:207]
	s_add_i32 m0, s94, 0xc000
	ds_read_b128 v[162:165], v228
	ds_read_b128 v[166:169], v228 offset:1024
	ds_read_b128 v[170:173], v228 offset:2048
	ds_read_b128 v[174:177], v228 offset:3072
	ds_read_b128 v[178:181], v228 offset:4096
	ds_read_b128 v[182:185], v228 offset:5120
	ds_read_b128 v[186:189], v228 offset:6144
	ds_read_b128 v[190:193], v228 offset:7168
	global_load_lds_dwordx4 v[212:213], off
	v_lshl_add_u64 v[212:213], s[14:15], 0, v[208:209]
	s_add_i32 m0, s94, 0xe000
	s_nop 0
	global_load_lds_dwordx4 v[212:213], off
	s_waitcnt vmcnt(8)
	s_waitcnt lgkmcnt(0)
	s_barrier
	s_setprio 1
	s_waitcnt lgkmcnt(0)
	v_mfma_f32_16x16x32_bf16 v[126:129], v[130:133], v[162:165], v[126:129]
	v_mfma_f32_16x16x32_bf16 v[122:125], v[138:141], v[162:165], v[122:125]
	v_mfma_f32_16x16x32_bf16 v[118:121], v[130:133], v[170:173], v[118:121]
	v_mfma_f32_16x16x32_bf16 v[114:117], v[138:141], v[170:173], v[114:117]
	v_mfma_f32_16x16x32_bf16 v[110:113], v[130:133], v[178:181], v[110:113]
	v_mfma_f32_16x16x32_bf16 v[106:109], v[138:141], v[178:181], v[106:109]
	v_mfma_f32_16x16x32_bf16 v[102:105], v[130:133], v[186:189], v[102:105]
	v_mfma_f32_16x16x32_bf16 v[98:101], v[138:141], v[186:189], v[98:101]
	v_mfma_f32_16x16x32_bf16 v[126:129], v[134:137], v[166:169], v[126:129]
	v_mfma_f32_16x16x32_bf16 v[122:125], v[142:145], v[166:169], v[122:125]
	v_mfma_f32_16x16x32_bf16 v[118:121], v[134:137], v[174:177], v[118:121]
	v_mfma_f32_16x16x32_bf16 v[114:117], v[142:145], v[174:177], v[114:117]
	v_mfma_f32_16x16x32_bf16 v[110:113], v[134:137], v[182:185], v[110:113]
	v_mfma_f32_16x16x32_bf16 v[106:109], v[142:145], v[182:185], v[106:109]
	v_mfma_f32_16x16x32_bf16 v[102:105], v[134:137], v[190:193], v[102:105]
	v_mfma_f32_16x16x32_bf16 v[98:101], v[142:145], v[190:193], v[98:101]
	s_setprio 0
	s_setprio 1
	v_mfma_f32_16x16x32_bf16 v[94:97], v[146:149], v[162:165], v[94:97]
	v_mfma_f32_16x16x32_bf16 v[90:93], v[154:157], v[162:165], v[90:93]
	v_mfma_f32_16x16x32_bf16 v[86:89], v[146:149], v[170:173], v[86:89]
	v_mfma_f32_16x16x32_bf16 v[82:85], v[154:157], v[170:173], v[82:85]
	v_mfma_f32_16x16x32_bf16 v[78:81], v[146:149], v[178:181], v[78:81]
	v_mfma_f32_16x16x32_bf16 v[74:77], v[154:157], v[178:181], v[74:77]
	v_mfma_f32_16x16x32_bf16 v[70:73], v[146:149], v[186:189], v[70:73]
	v_mfma_f32_16x16x32_bf16 v[66:69], v[154:157], v[186:189], v[66:69]
	v_mfma_f32_16x16x32_bf16 v[94:97], v[150:153], v[166:169], v[94:97]
	v_mfma_f32_16x16x32_bf16 v[90:93], v[158:161], v[166:169], v[90:93]
	v_mfma_f32_16x16x32_bf16 v[86:89], v[150:153], v[174:177], v[86:89]
	v_mfma_f32_16x16x32_bf16 v[82:85], v[158:161], v[174:177], v[82:85]
	v_mfma_f32_16x16x32_bf16 v[78:81], v[150:153], v[182:185], v[78:81]
	v_mfma_f32_16x16x32_bf16 v[74:77], v[158:161], v[182:185], v[74:77]
	v_mfma_f32_16x16x32_bf16 v[70:73], v[150:153], v[190:193], v[70:73]
	v_mfma_f32_16x16x32_bf16 v[66:69], v[158:161], v[190:193], v[66:69]
	s_setprio 0
	s_barrier
	s_add_i32 s14, s29, s93
	v_lshl_add_u64 v[212:213], s[16:17], 0, v[200:201]
	s_mov_b32 m0, s14
	ds_read_b128 v[162:165], v228 offset:16384
	ds_read_b128 v[166:169], v228 offset:17408
	ds_read_b128 v[170:173], v228 offset:18432
	ds_read_b128 v[174:177], v228 offset:19456
	ds_read_b128 v[178:181], v228 offset:20480
	ds_read_b128 v[182:185], v228 offset:21504
	ds_read_b128 v[186:189], v228 offset:22528
	ds_read_b128 v[190:193], v228 offset:23552
	global_load_lds_dwordx4 v[212:213], off
	s_add_i32 m0, s14, 0x2000
	s_add_u32 s14, s16, 0x40000
	v_lshl_add_u64 v[214:215], s[16:17], 0, v[204:205]
	s_addc_u32 s15, s17, 0
	s_add_i32 s45, s30, s93
	global_load_lds_dwordx4 v[214:215], off
	v_lshl_add_u64 v[216:217], s[14:15], 0, v[200:201]
	s_mov_b32 m0, s45
	v_lshl_add_u64 v[218:219], vcc, 0, v[202:203]
	global_load_lds_dwordx4 v[216:217], off
	v_lshl_add_u64 v[216:217], s[14:15], 0, v[204:205]
	s_add_i32 m0, s45, 0x2000
	s_nop 0
	global_load_lds_dwordx4 v[216:217], off
	v_lshl_add_u64 v[216:217], vcc, 0, v[198:199]
	s_mov_b32 m0, s94
	s_nop 0
	global_load_lds_dwordx4 v[216:217], off
	s_mov_b32 m0, s95
	s_nop 0
	global_load_lds_dwordx4 v[218:219], off
	s_waitcnt vmcnt(8)
	s_waitcnt lgkmcnt(0)
	s_barrier
; #define PG8_STAGE(bufoff, gbase, voff) do { _Pragma("unroll") for (int _i = 0; _i < 2; ++_i) \
;         __builtin_amdgcn_global_load_lds((const unsigned*)((const char*)(gbase) + (voff)[_i]), (LAS unsigned*)(lds + (bufoff) + ldsw + _i * 8192), 16, 0, 0); } while (0)
; #define PG8_LDA(dst, b, h) do { _Pragma("unroll") for (int m = 0; m < 4; ++m) _Pragma("unroll") for (int k = 0; k < 2; ++k) dst[m][k] = *(const LAS bf16x8*)(lds + PG8_SA(b, h) + aoff + m * 2048 + k * 1024); } while (0)
; #define PG8_LDB(dst, b, h) do { _Pragma("unroll") for (int n = 0; n < 2; ++n) _Pragma("unroll") for (int k = 0; k < 2; ++k) dst[n][k] = *(const LAS bf16x8*)(lds + PG8_SB(b, h) + boff + n * 2048 + k * 1024); } while (0)
; #define PG8_MMA(ai, bj, At, Bt) do { __builtin_amdgcn_s_setprio(1); _Pragma("unroll") for (int m = 0; m < 4; ++m) _Pragma("unroll") for (int n = 0; n < 2; ++n) _Pragma("unroll") for (int k = 0; k < 2; ++k) \
;         acc[ai][bj][m][n] = __builtin_amdgcn_mfma_f32_16x16x32_bf16(Bt[n][k], At[m][k], acc[ai][bj][m][n], 0, 0, 0); __builtin_amdgcn_s_setprio(0); } while (0)
; #define PG8_WAIT_V(n) asm volatile("s_waitcnt vmcnt(" #n ")" ::: "memory")
; #define PG8_WAIT_L(n) asm volatile("s_waitcnt lgkmcnt(" #n ")" ::: "memory")
; #define PG8_BAR __builtin_amdgcn_s_barrier()
; #define PG8_SCHED __builtin_amdgcn_sched_barrier(0)
; template <class Epi, int AC0, int BC0, int NT0, int AC1, int BC1, int NT1>
; __device__ __forceinline__ void gemm_phase(LAS unsigned char* lds, const Gemm g, const StaticOrder& S, const Epi& E, int tid) {
;     ...
;             PG8_WAIT_V(8); PG8_WAIT_L(0); PG8_BAR; PG8_MMA(1, 0, At, B0); PG8_MMA(1, 1, At, B1); PG8_BAR; PG8_SCHED;
;             PG8_LDB(B0, 1, 0); PG8_LDB(B1, 1, 1); PG8_SCHED; PG8_LDA(At, 1, 0); PG8_STAGE(PG8_SA(0, 1), a2 + hstepA, voffA);
;             PG8_WAIT_V(8); PG8_WAIT_L(0); PG8_BAR; PG8_MMA(0, 0, At, B0); PG8_MMA(0, 1, At, B1); PG8_BAR; PG8_SCHED;
	s_setprio 1
	s_waitcnt lgkmcnt(0)
	v_mfma_f32_16x16x32_bf16 v[62:65], v[130:133], v[162:165], v[62:65]
	v_mfma_f32_16x16x32_bf16 v[58:61], v[138:141], v[162:165], v[58:61]
	v_mfma_f32_16x16x32_bf16 v[54:57], v[130:133], v[170:173], v[54:57]
	v_mfma_f32_16x16x32_bf16 v[50:53], v[138:141], v[170:173], v[50:53]
	v_mfma_f32_16x16x32_bf16 v[46:49], v[130:133], v[178:181], v[46:49]
	v_mfma_f32_16x16x32_bf16 v[42:45], v[138:141], v[178:181], v[42:45]
	v_mfma_f32_16x16x32_bf16 v[38:41], v[130:133], v[186:189], v[38:41]
	v_mfma_f32_16x16x32_bf16 v[34:37], v[138:141], v[186:189], v[34:37]
	v_mfma_f32_16x16x32_bf16 v[62:65], v[134:137], v[166:169], v[62:65]
	v_mfma_f32_16x16x32_bf16 v[58:61], v[142:145], v[166:169], v[58:61]
	v_mfma_f32_16x16x32_bf16 v[54:57], v[134:137], v[174:177], v[54:57]
	v_mfma_f32_16x16x32_bf16 v[50:53], v[142:145], v[174:177], v[50:53]
	v_mfma_f32_16x16x32_bf16 v[46:49], v[134:137], v[182:185], v[46:49]
	v_mfma_f32_16x16x32_bf16 v[42:45], v[142:145], v[182:185], v[42:45]
	v_mfma_f32_16x16x32_bf16 v[38:41], v[134:137], v[190:193], v[38:41]
	v_mfma_f32_16x16x32_bf16 v[34:37], v[142:145], v[190:193], v[34:37]
	s_setprio 0
	s_setprio 1
	v_mfma_f32_16x16x32_bf16 v[30:33], v[146:149], v[162:165], v[30:33]
	v_mfma_f32_16x16x32_bf16 v[26:29], v[154:157], v[162:165], v[26:29]
	v_mfma_f32_16x16x32_bf16 v[22:25], v[146:149], v[170:173], v[22:25]
	v_mfma_f32_16x16x32_bf16 v[18:21], v[154:157], v[170:173], v[18:21]
	v_mfma_f32_16x16x32_bf16 v[14:17], v[146:149], v[178:181], v[14:17]
	v_mfma_f32_16x16x32_bf16 v[10:13], v[154:157], v[178:181], v[10:13]
	v_mfma_f32_16x16x32_bf16 v[6:9], v[146:149], v[186:189], v[6:9]
	v_mfma_f32_16x16x32_bf16 v[2:5], v[154:157], v[186:189], v[2:5]
	v_mfma_f32_16x16x32_bf16 v[30:33], v[150:153], v[166:169], v[30:33]
	v_mfma_f32_16x16x32_bf16 v[26:29], v[158:161], v[166:169], v[26:29]
	v_mfma_f32_16x16x32_bf16 v[22:25], v[150:153], v[174:177], v[22:25]
	v_mfma_f32_16x16x32_bf16 v[18:21], v[158:161], v[174:177], v[18:21]
	v_mfma_f32_16x16x32_bf16 v[14:17], v[150:153], v[182:185], v[14:17]
	v_mfma_f32_16x16x32_bf16 v[10:13], v[158:161], v[182:185], v[10:13]
	v_mfma_f32_16x16x32_bf16 v[6:9], v[150:153], v[190:193], v[6:9]
	v_mfma_f32_16x16x32_bf16 v[2:5], v[158:161], v[190:193], v[2:5]
	s_setprio 0
	s_barrier
	s_add_i32 s45, 0, 0x18000
	s_add_i32 s52, 0, 0x1c000
	v_add_u32_e32 v142, s45, v222
	v_add_u32_e32 v158, s52, v222
	ds_read_b128 v[130:133], v142
	ds_read_b128 v[134:137], v142 offset:1024
	ds_read_b128 v[138:141], v142 offset:2048
	ds_read_b128 v[142:145], v142 offset:3072
	ds_read_b128 v[146:149], v158
	ds_read_b128 v[150:153], v158 offset:1024
	ds_read_b128 v[154:157], v158 offset:2048
	ds_read_b128 v[158:161], v158 offset:3072
	s_add_u32 s14, vcc_lo, 0x150000
	s_addc_u32 s15, vcc_hi, 0
	s_mov_b32 m0, s24
	v_lshl_add_u64 v[220:221], s[14:15], 0, v[198:199]
	ds_read_b128 v[162:165], v228 offset:32768
	ds_read_b128 v[166:169], v228 offset:33792
	ds_read_b128 v[170:173], v228 offset:34816
	ds_read_b128 v[174:177], v228 offset:35840
	ds_read_b128 v[178:181], v228 offset:36864
	ds_read_b128 v[182:185], v228 offset:37888
	ds_read_b128 v[186:189], v228 offset:38912
	ds_read_b128 v[190:193], v228 offset:39936
	global_load_lds_dwordx4 v[220:221], off
	v_lshl_add_u64 v[220:221], s[14:15], 0, v[202:203]
	s_mov_b32 m0, s25
	s_nop 0
	global_load_lds_dwordx4 v[220:221], off
	s_waitcnt vmcnt(8)
	s_waitcnt lgkmcnt(0)
	s_barrier
	s_setprio 1
	s_waitcnt lgkmcnt(0)
	v_mfma_f32_16x16x32_bf16 v[126:129], v[130:133], v[162:165], v[126:129]
	v_mfma_f32_16x16x32_bf16 v[122:125], v[138:141], v[162:165], v[122:125]
	v_mfma_f32_16x16x32_bf16 v[118:121], v[130:133], v[170:173], v[118:121]
	v_mfma_f32_16x16x32_bf16 v[114:117], v[138:141], v[170:173], v[114:117]
	v_mfma_f32_16x16x32_bf16 v[110:113], v[130:133], v[178:181], v[110:113]
	v_mfma_f32_16x16x32_bf16 v[106:109], v[138:141], v[178:181], v[106:109]
	v_mfma_f32_16x16x32_bf16 v[102:105], v[130:133], v[186:189], v[102:105]
	v_mfma_f32_16x16x32_bf16 v[98:101], v[138:141], v[186:189], v[98:101]
	v_mfma_f32_16x16x32_bf16 v[126:129], v[134:137], v[166:169], v[126:129]
	v_mfma_f32_16x16x32_bf16 v[122:125], v[142:145], v[166:169], v[122:125]
	v_mfma_f32_16x16x32_bf16 v[118:121], v[134:137], v[174:177], v[118:121]
	v_mfma_f32_16x16x32_bf16 v[114:117], v[142:145], v[174:177], v[114:117]
	v_mfma_f32_16x16x32_bf16 v[110:113], v[134:137], v[182:185], v[110:113]
	v_mfma_f32_16x16x32_bf16 v[106:109], v[142:145], v[182:185], v[106:109]
	v_mfma_f32_16x16x32_bf16 v[102:105], v[134:137], v[190:193], v[102:105]
	v_mfma_f32_16x16x32_bf16 v[98:101], v[142:145], v[190:193], v[98:101]
	s_setprio 0
	s_setprio 1
	v_mfma_f32_16x16x32_bf16 v[94:97], v[146:149], v[162:165], v[94:97]
	v_mfma_f32_16x16x32_bf16 v[90:93], v[154:157], v[162:165], v[90:93]
	v_mfma_f32_16x16x32_bf16 v[86:89], v[146:149], v[170:173], v[86:89]
	v_mfma_f32_16x16x32_bf16 v[82:85], v[154:157], v[170:173], v[82:85]
	v_mfma_f32_16x16x32_bf16 v[78:81], v[146:149], v[178:181], v[78:81]
	v_mfma_f32_16x16x32_bf16 v[74:77], v[154:157], v[178:181], v[74:77]
	v_mfma_f32_16x16x32_bf16 v[70:73], v[146:149], v[186:189], v[70:73]
	v_mfma_f32_16x16x32_bf16 v[66:69], v[154:157], v[186:189], v[66:69]
	v_mfma_f32_16x16x32_bf16 v[94:97], v[150:153], v[166:169], v[94:97]
	v_mfma_f32_16x16x32_bf16 v[90:93], v[158:161], v[166:169], v[90:93]
	v_mfma_f32_16x16x32_bf16 v[86:89], v[150:153], v[174:177], v[86:89]
	v_mfma_f32_16x16x32_bf16 v[82:85], v[158:161], v[174:177], v[82:85]
	v_mfma_f32_16x16x32_bf16 v[78:81], v[150:153], v[182:185], v[78:81]
	v_mfma_f32_16x16x32_bf16 v[74:77], v[158:161], v[182:185], v[74:77]
	v_mfma_f32_16x16x32_bf16 v[70:73], v[150:153], v[190:193], v[70:73]
	v_mfma_f32_16x16x32_bf16 v[66:69], v[158:161], v[190:193], v[66:69]
	s_setprio 0
	s_barrier
; #define PG8_STAGE(bufoff, gbase, voff) do { _Pragma("unroll") for (int _i = 0; _i < 2; ++_i) \
;         __builtin_amdgcn_global_load_lds((const unsigned*)((const char*)(gbase) + (voff)[_i]), (LAS unsigned*)(lds + (bufoff) + ldsw + _i * 8192), 16, 0, 0); } while (0)
; #define PG8_LDA(dst, b, h) do { _Pragma("unroll") for (int m = 0; m < 4; ++m) _Pragma("unroll") for (int k = 0; k < 2; ++k) dst[m][k] = *(const LAS bf16x8*)(lds + PG8_SA(b, h) + aoff + m * 2048 + k * 1024); } while (0)
; #define PG8_MMA(ai, bj, At, Bt) do { __builtin_amdgcn_s_setprio(1); _Pragma("unroll") for (int m = 0; m < 4; ++m) _Pragma("unroll") for (int n = 0; n < 2; ++n) _Pragma("unroll") for (int k = 0; k < 2; ++k) \
;         acc[ai][bj][m][n] = __builtin_amdgcn_mfma_f32_16x16x32_bf16(Bt[n][k], At[m][k], acc[ai][bj][m][n], 0, 0, 0); __builtin_amdgcn_s_setprio(0); } while (0)
; #define PG8_WAIT_V(n) asm volatile("s_waitcnt vmcnt(" #n ")" ::: "memory")
; #define PG8_WAIT_L(n) asm volatile("s_waitcnt lgkmcnt(" #n ")" ::: "memory")
; #define PG8_BAR __builtin_amdgcn_s_barrier()
; #define PG8_SCHED __builtin_amdgcn_sched_barrier(0)
; template <class Epi, int AC0, int BC0, int NT0, int AC1, int BC1, int NT1>
; __device__ __forceinline__ void gemm_phase(LAS unsigned char* lds, const Gemm g, const StaticOrder& S, const Epi& E, int tid) {
;     ...
;             PG8_LDA(At, 1, 1); PG8_STAGE(PG8_SB(1, 0), b3, voffB); PG8_STAGE(PG8_SB(1, 1), b3 + hstepB, voffB); PG8_STAGE(PG8_SA(1, 0), a3, voffA);
;             PG8_WAIT_V(8); PG8_WAIT_L(0); PG8_BAR; PG8_MMA(1, 0, At, B0); PG8_MMA(1, 1, At, B1); PG8_BAR; PG8_SCHED;
;         }
	s_add_i32 s14, s45, s93
	v_lshl_add_u64 v[212:213], v[212:213], 0, s[4:5]
	s_mov_b32 m0, s14
	ds_read_b128 v[162:165], v228 offset:49152
	ds_read_b128 v[166:169], v228 offset:50176
	ds_read_b128 v[170:173], v228 offset:51200
	ds_read_b128 v[174:177], v228 offset:52224
	ds_read_b128 v[178:181], v228 offset:53248
	ds_read_b128 v[182:185], v228 offset:54272
	ds_read_b128 v[186:189], v228 offset:55296
	ds_read_b128 v[190:193], v228 offset:56320
	global_load_lds_dwordx4 v[212:213], off
	s_add_i32 m0, s14, 0x2000
	s_add_u32 s14, s16, 0x40080
	v_lshl_add_u64 v[212:213], v[214:215], 0, s[4:5]
	s_addc_u32 s15, s17, 0
	s_add_i32 s16, s52, s93
	global_load_lds_dwordx4 v[212:213], off
	v_lshl_add_u64 v[212:213], s[14:15], 0, v[200:201]
	s_mov_b32 m0, s16
	s_nop 0
	global_load_lds_dwordx4 v[212:213], off
	v_lshl_add_u64 v[212:213], s[14:15], 0, v[204:205]
	s_add_i32 m0, s16, 0x2000
	s_nop 0
	global_load_lds_dwordx4 v[212:213], off
	v_lshl_add_u64 v[212:213], v[216:217], 0, s[4:5]
	s_mov_b32 m0, s26
	s_nop 0
	global_load_lds_dwordx4 v[212:213], off
	v_lshl_add_u64 v[212:213], v[218:219], 0, s[4:5]
	s_mov_b32 m0, s27
	s_nop 0
	global_load_lds_dwordx4 v[212:213], off
	s_waitcnt vmcnt(8)
	s_waitcnt lgkmcnt(0)
	s_barrier
	s_setprio 1
	s_waitcnt lgkmcnt(0)
	v_mfma_f32_16x16x32_bf16 v[62:65], v[130:133], v[162:165], v[62:65]
	v_mfma_f32_16x16x32_bf16 v[58:61], v[138:141], v[162:165], v[58:61]
	v_mfma_f32_16x16x32_bf16 v[54:57], v[130:133], v[170:173], v[54:57]
	v_mfma_f32_16x16x32_bf16 v[50:53], v[138:141], v[170:173], v[50:53]
	v_mfma_f32_16x16x32_bf16 v[46:49], v[130:133], v[178:181], v[46:49]
	v_mfma_f32_16x16x32_bf16 v[42:45], v[138:141], v[178:181], v[42:45]
	v_mfma_f32_16x16x32_bf16 v[38:41], v[130:133], v[186:189], v[38:41]
	v_mfma_f32_16x16x32_bf16 v[34:37], v[138:141], v[186:189], v[34:37]
	v_mfma_f32_16x16x32_bf16 v[62:65], v[134:137], v[166:169], v[62:65]
	v_mfma_f32_16x16x32_bf16 v[58:61], v[142:145], v[166:169], v[58:61]
	v_mfma_f32_16x16x32_bf16 v[54:57], v[134:137], v[174:177], v[54:57]
	v_mfma_f32_16x16x32_bf16 v[50:53], v[142:145], v[174:177], v[50:53]
	v_mfma_f32_16x16x32_bf16 v[46:49], v[134:137], v[182:185], v[46:49]
	v_mfma_f32_16x16x32_bf16 v[42:45], v[142:145], v[182:185], v[42:45]
	v_mfma_f32_16x16x32_bf16 v[38:41], v[134:137], v[190:193], v[38:41]
	v_mfma_f32_16x16x32_bf16 v[34:37], v[142:145], v[190:193], v[34:37]
	s_setprio 0
	s_setprio 1
	v_mfma_f32_16x16x32_bf16 v[30:33], v[146:149], v[162:165], v[30:33]
	v_mfma_f32_16x16x32_bf16 v[26:29], v[154:157], v[162:165], v[26:29]
	v_mfma_f32_16x16x32_bf16 v[22:25], v[146:149], v[170:173], v[22:25]
	v_mfma_f32_16x16x32_bf16 v[18:21], v[154:157], v[170:173], v[18:21]
	v_mfma_f32_16x16x32_bf16 v[14:17], v[146:149], v[178:181], v[14:17]
	v_mfma_f32_16x16x32_bf16 v[10:13], v[154:157], v[178:181], v[10:13]
	v_mfma_f32_16x16x32_bf16 v[6:9], v[146:149], v[186:189], v[6:9]
	v_mfma_f32_16x16x32_bf16 v[2:5], v[154:157], v[186:189], v[2:5]
	v_mfma_f32_16x16x32_bf16 v[30:33], v[150:153], v[166:169], v[30:33]
	v_mfma_f32_16x16x32_bf16 v[26:29], v[158:161], v[166:169], v[26:29]
	v_mfma_f32_16x16x32_bf16 v[22:25], v[150:153], v[174:177], v[22:25]
	v_mfma_f32_16x16x32_bf16 v[18:21], v[158:161], v[174:177], v[18:21]
	v_mfma_f32_16x16x32_bf16 v[14:17], v[150:153], v[182:185], v[14:17]
	v_mfma_f32_16x16x32_bf16 v[10:13], v[158:161], v[182:185], v[10:13]
	v_mfma_f32_16x16x32_bf16 v[6:9], v[150:153], v[190:193], v[6:9]
	v_mfma_f32_16x16x32_bf16 v[2:5], v[158:161], v[190:193], v[2:5]
	s_add_i32 s42, s42, 2
	s_add_u32 s33, s33, 0x100
	s_addc_u32 s37, s37, 0
	s_cmp_gt_u32 s42, 5
	s_mov_b64 s[14:15], s[0:1]
	s_setprio 0
	s_barrier
	s_cbranch_scc0 .LBB0_725
	s_and_b64 vcc, exec, s[6:7]
	s_cbranch_vccz .LBB0_728
	s_barrier

; #define PG8_STAGE(bufoff, gbase, voff) do { _Pragma("unroll") for (int _i = 0; _i < 2; ++_i) \
;         __builtin_amdgcn_global_load_lds((const unsigned*)((const char*)(gbase) + (voff)[_i]), (LAS unsigned*)(lds + (bufoff) + ldsw + _i * 8192), 16, 0, 0); } while (0)
; #define PG8_LDA(dst, b, h) do { _Pragma("unroll") for (int m = 0; m < 4; ++m) _Pragma("unroll") for (int k = 0; k < 2; ++k) dst[m][k] = *(const LAS bf16x8*)(lds + PG8_SA(b, h) + aoff + m * 2048 + k * 1024); } while (0)
; #define PG8_LDB(dst, b, h) do { _Pragma("unroll") for (int n = 0; n < 2; ++n) _Pragma("unroll") for (int k = 0; k < 2; ++k) dst[n][k] = *(const LAS bf16x8*)(lds + PG8_SB(b, h) + boff + n * 2048 + k * 1024); } while (0)
; #define PG8_MMA(ai, bj, At, Bt) do { __builtin_amdgcn_s_setprio(1); _Pragma("unroll") for (int m = 0; m < 4; ++m) _Pragma("unroll") for (int n = 0; n < 2; ++n) _Pragma("unroll") for (int k = 0; k < 2; ++k) \
;         acc[ai][bj][m][n] = __builtin_amdgcn_mfma_f32_16x16x32_bf16(Bt[n][k], At[m][k], acc[ai][bj][m][n], 0, 0, 0); __builtin_amdgcn_s_setprio(0); } while (0)
; #define PG8_WAIT_V(n) asm volatile("s_waitcnt vmcnt(" #n ")" ::: "memory")
; #define PG8_WAIT_L(n) asm volatile("s_waitcnt lgkmcnt(" #n ")" ::: "memory")
; #define PG8_BAR __builtin_amdgcn_s_barrier()
; #define PG8_SCHED __builtin_amdgcn_sched_barrier(0)
; template <class Epi, int AC0, int BC0, int NT0, int AC1, int BC1, int NT1>
; __device__ __forceinline__ void gemm_phase(LAS unsigned char* lds, const Gemm g, const StaticOrder& S, const Epi& E, int tid) {
;     ...
;             PG8_LDB(B0, 1, 0); PG8_LDB(B1, 1, 1); PG8_SCHED; PG8_LDA(At, 1, 0); PG8_STAGE(PG8_SA(0, 1), a2 + hstepA, voffA);
;             PG8_WAIT_V(8); PG8_WAIT_L(0); PG8_BAR; PG8_MMA(0, 0, At, B0); PG8_MMA(0, 1, At, B1); PG8_BAR; PG8_SCHED;
.Lmid_P4:
	s_add_i32 s75, 0, 0x18000
	s_add_i32 s76, 0, 0x1c000
	v_add_u32_e32 v142, s75, v216
	v_add_u32_e32 v158, s76, v216
	ds_read_b128 v[130:133], v142
	ds_read_b128 v[134:137], v142 offset:1024
	ds_read_b128 v[138:141], v142 offset:2048
	ds_read_b128 v[142:145], v142 offset:3072
	ds_read_b128 v[146:149], v158
	ds_read_b128 v[150:153], v158 offset:1024
	ds_read_b128 v[154:157], v158 offset:2048
	ds_read_b128 v[158:161], v158 offset:3072
	s_add_u32 s66, s66, 0x40000
	s_addc_u32 s67, s67, 0
	s_mov_b32 m0, s28
	v_lshl_add_u64 v[226:227], s[66:67], 0, v[186:187]
	ds_read_b128 v[162:165], v220 offset:32768
	ds_read_b128 v[166:169], v220 offset:33792
	ds_read_b128 v[170:173], v220 offset:34816
	ds_read_b128 v[174:177], v220 offset:35840
	ds_read_b128 v[178:181], v220 offset:36864
	ds_read_b128 v[182:185], v220 offset:37888
	ds_read_b128 v[204:207], v220 offset:38912
	ds_read_b128 v[208:211], v220 offset:39936
	global_load_lds_dwordx4 v[226:227], off
	v_lshl_add_u64 v[226:227], s[66:67], 0, v[190:191]
	s_mov_b32 m0, s29
	s_nop 0
	global_load_lds_dwordx4 v[226:227], off
	s_waitcnt vmcnt(8)
	s_waitcnt lgkmcnt(0)
	s_barrier
	s_setprio 1
	s_waitcnt lgkmcnt(0)
	v_mfma_f32_16x16x32_bf16 v[126:129], v[130:133], v[162:165], v[126:129]
	v_mfma_f32_16x16x32_bf16 v[122:125], v[138:141], v[162:165], v[122:125]
	v_mfma_f32_16x16x32_bf16 v[110:113], v[130:133], v[170:173], v[110:113]
	v_mfma_f32_16x16x32_bf16 v[106:109], v[138:141], v[170:173], v[106:109]
	v_mfma_f32_16x16x32_bf16 v[94:97], v[130:133], v[178:181], v[94:97]
	v_mfma_f32_16x16x32_bf16 v[90:93], v[138:141], v[178:181], v[90:93]
	v_mfma_f32_16x16x32_bf16 v[78:81], v[130:133], v[204:207], v[78:81]
	v_mfma_f32_16x16x32_bf16 v[74:77], v[138:141], v[204:207], v[74:77]
	v_mfma_f32_16x16x32_bf16 v[126:129], v[134:137], v[166:169], v[126:129]
	v_mfma_f32_16x16x32_bf16 v[122:125], v[142:145], v[166:169], v[122:125]
	v_mfma_f32_16x16x32_bf16 v[110:113], v[134:137], v[174:177], v[110:113]
	v_mfma_f32_16x16x32_bf16 v[106:109], v[142:145], v[174:177], v[106:109]
	v_mfma_f32_16x16x32_bf16 v[94:97], v[134:137], v[182:185], v[94:97]
	v_mfma_f32_16x16x32_bf16 v[90:93], v[142:145], v[182:185], v[90:93]
	v_mfma_f32_16x16x32_bf16 v[78:81], v[134:137], v[208:211], v[78:81]
	v_mfma_f32_16x16x32_bf16 v[74:77], v[142:145], v[208:211], v[74:77]
	s_setprio 0
	s_setprio 1
	v_mfma_f32_16x16x32_bf16 v[118:121], v[146:149], v[162:165], v[118:121]
	v_mfma_f32_16x16x32_bf16 v[114:117], v[154:157], v[162:165], v[114:117]
	v_mfma_f32_16x16x32_bf16 v[102:105], v[146:149], v[170:173], v[102:105]
	v_mfma_f32_16x16x32_bf16 v[98:101], v[154:157], v[170:173], v[98:101]
	v_mfma_f32_16x16x32_bf16 v[86:89], v[146:149], v[178:181], v[86:89]
	v_mfma_f32_16x16x32_bf16 v[82:85], v[154:157], v[178:181], v[82:85]
	v_mfma_f32_16x16x32_bf16 v[70:73], v[146:149], v[204:207], v[70:73]
	v_mfma_f32_16x16x32_bf16 v[66:69], v[154:157], v[204:207], v[66:69]
	v_mfma_f32_16x16x32_bf16 v[118:121], v[150:153], v[166:169], v[118:121]
	v_mfma_f32_16x16x32_bf16 v[114:117], v[158:161], v[166:169], v[114:117]
	v_mfma_f32_16x16x32_bf16 v[102:105], v[150:153], v[174:177], v[102:105]
	v_mfma_f32_16x16x32_bf16 v[98:101], v[158:161], v[174:177], v[98:101]
	v_mfma_f32_16x16x32_bf16 v[86:89], v[150:153], v[182:185], v[86:89]
	v_mfma_f32_16x16x32_bf16 v[82:85], v[158:161], v[182:185], v[82:85]
	v_mfma_f32_16x16x32_bf16 v[70:73], v[150:153], v[208:211], v[70:73]
	v_mfma_f32_16x16x32_bf16 v[66:69], v[158:161], v[208:211], v[66:69]
	s_setprio 0
	s_barrier
; #define PG8_STAGE(bufoff, gbase, voff) do { _Pragma("unroll") for (int _i = 0; _i < 2; ++_i) \
;         __builtin_amdgcn_global_load_lds((const unsigned*)((const char*)(gbase) + (voff)[_i]), (LAS unsigned*)(lds + (bufoff) + ldsw + _i * 8192), 16, 0, 0); } while (0)
; #define PG8_LDA(dst, b, h) do { _Pragma("unroll") for (int m = 0; m < 4; ++m) _Pragma("unroll") for (int k = 0; k < 2; ++k) dst[m][k] = *(const LAS bf16x8*)(lds + PG8_SA(b, h) + aoff + m * 2048 + k * 1024); } while (0)
; #define PG8_MMA(ai, bj, At, Bt) do { __builtin_amdgcn_s_setprio(1); _Pragma("unroll") for (int m = 0; m < 4; ++m) _Pragma("unroll") for (int n = 0; n < 2; ++n) _Pragma("unroll") for (int k = 0; k < 2; ++k) \
;         acc[ai][bj][m][n] = __builtin_amdgcn_mfma_f32_16x16x32_bf16(Bt[n][k], At[m][k], acc[ai][bj][m][n], 0, 0, 0); __builtin_amdgcn_s_setprio(0); } while (0)
; #define PG8_WAIT_V(n) asm volatile("s_waitcnt vmcnt(" #n ")" ::: "memory")
; #define PG8_WAIT_L(n) asm volatile("s_waitcnt lgkmcnt(" #n ")" ::: "memory")
; #define PG8_BAR __builtin_amdgcn_s_barrier()
; #define PG8_SCHED __builtin_amdgcn_sched_barrier(0)
; template <class Epi, int AC0, int BC0, int NT0, int AC1, int BC1, int NT1>
; __device__ __forceinline__ void gemm_phase(LAS unsigned char* lds, const Gemm g, const StaticOrder& S, const Epi& E, int tid) {
;     ...
;             PG8_LDA(At, 1, 1); PG8_STAGE(PG8_SB(1, 0), b3, voffB); PG8_STAGE(PG8_SB(1, 1), b3 + hstepB, voffB); PG8_STAGE(PG8_SA(1, 0), a3, voffA);
;             PG8_WAIT_V(8); PG8_WAIT_L(0); PG8_BAR; PG8_MMA(1, 0, At, B0); PG8_MMA(1, 1, At, B1); PG8_BAR; PG8_SCHED;
;         }
	s_add_i32 s66, s75, s25
	v_lshl_add_u64 v[212:213], v[212:213], 0, s[6:7]
	s_mov_b32 m0, s66
	ds_read_b128 v[162:165], v220 offset:49152
	ds_read_b128 v[166:169], v220 offset:50176
	ds_read_b128 v[170:173], v220 offset:51200
	ds_read_b128 v[174:177], v220 offset:52224
	ds_read_b128 v[178:181], v220 offset:53248
	ds_read_b128 v[182:185], v220 offset:54272
	ds_read_b128 v[204:207], v220 offset:55296
	ds_read_b128 v[208:211], v220 offset:56320
	global_load_lds_dwordx4 v[212:213], off
	s_add_i32 m0, s66, 0x2000
	s_add_u32 s20, s20, 0x40080
	v_lshl_add_u64 v[212:213], v[214:215], 0, s[6:7]
	s_addc_u32 s21, s21, 0
	s_add_i32 s66, s76, s25
	global_load_lds_dwordx4 v[212:213], off
	v_lshl_add_u64 v[212:213], s[20:21], 0, v[188:189]
	s_mov_b32 m0, s66
	s_nop 0
	global_load_lds_dwordx4 v[212:213], off
	v_lshl_add_u64 v[212:213], s[20:21], 0, v[192:193]
	s_add_i32 m0, s66, 0x2000
	s_nop 0
	global_load_lds_dwordx4 v[212:213], off
	v_lshl_add_u64 v[212:213], v[222:223], 0, s[6:7]
	s_mov_b32 m0, s35
	s_nop 0
	global_load_lds_dwordx4 v[212:213], off
	v_lshl_add_u64 v[212:213], v[224:225], 0, s[6:7]
	s_mov_b32 m0, s36
	s_nop 0
	global_load_lds_dwordx4 v[212:213], off
	s_waitcnt vmcnt(8)
	s_waitcnt lgkmcnt(0)
	s_barrier
	s_setprio 1
	s_waitcnt lgkmcnt(0)
	v_mfma_f32_16x16x32_bf16 v[62:65], v[130:133], v[162:165], v[62:65]
	v_mfma_f32_16x16x32_bf16 v[58:61], v[138:141], v[162:165], v[58:61]
	v_mfma_f32_16x16x32_bf16 v[46:49], v[130:133], v[170:173], v[46:49]
	v_mfma_f32_16x16x32_bf16 v[42:45], v[138:141], v[170:173], v[42:45]
	v_mfma_f32_16x16x32_bf16 v[30:33], v[130:133], v[178:181], v[30:33]
	v_mfma_f32_16x16x32_bf16 v[26:29], v[138:141], v[178:181], v[26:29]
	v_mfma_f32_16x16x32_bf16 v[14:17], v[130:133], v[204:207], v[14:17]
	v_mfma_f32_16x16x32_bf16 v[10:13], v[138:141], v[204:207], v[10:13]
	v_mfma_f32_16x16x32_bf16 v[62:65], v[134:137], v[166:169], v[62:65]
	v_mfma_f32_16x16x32_bf16 v[58:61], v[142:145], v[166:169], v[58:61]
	v_mfma_f32_16x16x32_bf16 v[46:49], v[134:137], v[174:177], v[46:49]
	v_mfma_f32_16x16x32_bf16 v[42:45], v[142:145], v[174:177], v[42:45]
	v_mfma_f32_16x16x32_bf16 v[30:33], v[134:137], v[182:185], v[30:33]
	v_mfma_f32_16x16x32_bf16 v[26:29], v[142:145], v[182:185], v[26:29]
	v_mfma_f32_16x16x32_bf16 v[14:17], v[134:137], v[208:211], v[14:17]
	v_mfma_f32_16x16x32_bf16 v[10:13], v[142:145], v[208:211], v[10:13]
	s_setprio 0
	s_setprio 1
	v_mfma_f32_16x16x32_bf16 v[54:57], v[146:149], v[162:165], v[54:57]
	v_mfma_f32_16x16x32_bf16 v[50:53], v[154:157], v[162:165], v[50:53]
	v_mfma_f32_16x16x32_bf16 v[38:41], v[146:149], v[170:173], v[38:41]
	v_mfma_f32_16x16x32_bf16 v[34:37], v[154:157], v[170:173], v[34:37]
	v_mfma_f32_16x16x32_bf16 v[22:25], v[146:149], v[178:181], v[22:25]
	v_mfma_f32_16x16x32_bf16 v[18:21], v[154:157], v[178:181], v[18:21]
	v_mfma_f32_16x16x32_bf16 v[6:9], v[146:149], v[204:207], v[6:9]
	v_mfma_f32_16x16x32_bf16 v[2:5], v[154:157], v[204:207], v[2:5]
	v_mfma_f32_16x16x32_bf16 v[54:57], v[150:153], v[166:169], v[54:57]
	v_mfma_f32_16x16x32_bf16 v[50:53], v[158:161], v[166:169], v[50:53]
	v_mfma_f32_16x16x32_bf16 v[38:41], v[150:153], v[174:177], v[38:41]
	v_mfma_f32_16x16x32_bf16 v[34:37], v[158:161], v[174:177], v[34:37]
	v_mfma_f32_16x16x32_bf16 v[22:25], v[150:153], v[182:185], v[22:25]
	v_mfma_f32_16x16x32_bf16 v[18:21], v[158:161], v[182:185], v[18:21]
	v_mfma_f32_16x16x32_bf16 v[6:9], v[150:153], v[208:211], v[6:9]
	v_mfma_f32_16x16x32_bf16 v[2:5], v[158:161], v[208:211], v[2:5]
	s_add_i32 s73, s73, 2
	s_add_u32 s18, s18, 0x100
	s_addc_u32 s19, s19, 0
	s_add_u32 s15, s15, 0x100
	s_addc_u32 s33, s33, 0
	s_cmp_gt_u32 s73, 13
	s_setprio 0
	s_barrier
	s_cbranch_scc0 .LBB0_899
	s_and_b64 vcc, exec, s[10:11]
	s_cbranch_vccz .LBB0_902
	s_barrier

; #define PG8_STAGE(bufoff, gbase, voff) do { _Pragma("unroll") for (int _i = 0; _i < 2; ++_i) \
;         __builtin_amdgcn_global_load_lds((const unsigned*)((const char*)(gbase) + (voff)[_i]), (LAS unsigned*)(lds + (bufoff) + ldsw + _i * 8192), 16, 0, 0); } while (0)
; #define PG8_LDA(dst, b, h) do { _Pragma("unroll") for (int m = 0; m < 4; ++m) _Pragma("unroll") for (int k = 0; k < 2; ++k) dst[m][k] = *(const LAS bf16x8*)(lds + PG8_SA(b, h) + aoff + m * 2048 + k * 1024); } while (0)
; #define PG8_LDB(dst, b, h) do { _Pragma("unroll") for (int n = 0; n < 2; ++n) _Pragma("unroll") for (int k = 0; k < 2; ++k) dst[n][k] = *(const LAS bf16x8*)(lds + PG8_SB(b, h) + boff + n * 2048 + k * 1024); } while (0)
; #define PG8_MMA(ai, bj, At, Bt) do { __builtin_amdgcn_s_setprio(1); _Pragma("unroll") for (int m = 0; m < 4; ++m) _Pragma("unroll") for (int n = 0; n < 2; ++n) _Pragma("unroll") for (int k = 0; k < 2; ++k) \
;         acc[ai][bj][m][n] = __builtin_amdgcn_mfma_f32_16x16x32_bf16(Bt[n][k], At[m][k], acc[ai][bj][m][n], 0, 0, 0); __builtin_amdgcn_s_setprio(0); } while (0)
; #define PG8_WAIT_V(n) asm volatile("s_waitcnt vmcnt(" #n ")" ::: "memory")
; #define PG8_WAIT_L(n) asm volatile("s_waitcnt lgkmcnt(" #n ")" ::: "memory")
; #define PG8_BAR __builtin_amdgcn_s_barrier()
; #define PG8_SCHED __builtin_amdgcn_sched_barrier(0)
; template <class Epi, int AC0, int BC0, int NT0, int AC1, int BC1, int NT1>
; __device__ __forceinline__ void gemm_phase(LAS unsigned char* lds, const Gemm g, const StaticOrder& S, const Epi& E, int tid) {
;     ...
;             PG8_LDB(B0, 1, 0); PG8_LDB(B1, 1, 1); PG8_SCHED; PG8_LDA(At, 1, 0); PG8_STAGE(PG8_SA(0, 1), a2 + hstepA, voffA);
;             PG8_WAIT_V(8); PG8_WAIT_L(0); PG8_BAR; PG8_MMA(0, 0, At, B0); PG8_MMA(0, 1, At, B1); PG8_BAR; PG8_SCHED;
.Lmid_P5:
	s_add_i32 s51, 0, 0x18000
	s_add_i32 s52, 0, 0x1c000
	v_add_u32_e32 v140, s51, v221
	v_add_u32_e32 v156, s52, v221
	ds_read_b128 v[128:131], v140
	ds_read_b128 v[132:135], v140 offset:1024
	ds_read_b128 v[136:139], v140 offset:2048
	ds_read_b128 v[140:143], v140 offset:3072
	ds_read_b128 v[144:147], v156
	ds_read_b128 v[148:151], v156 offset:1024
	ds_read_b128 v[152:155], v156 offset:2048
	ds_read_b128 v[156:159], v156 offset:3072
	s_add_u32 s18, s24, 0x50000
	s_addc_u32 s19, s25, 0
	s_mov_b32 m0, s30
	v_lshl_add_u64 v[214:215], s[18:19], 0, v[192:193]
	ds_read_b128 v[160:163], v233 offset:32768
	ds_read_b128 v[164:167], v233 offset:33792
	ds_read_b128 v[168:171], v233 offset:34816
	ds_read_b128 v[172:175], v233 offset:35840
	ds_read_b128 v[176:179], v233 offset:36864
	ds_read_b128 v[180:183], v233 offset:37888
	ds_read_b128 v[184:187], v233 offset:38912
	ds_read_b128 v[188:191], v233 offset:39936
	global_load_lds_dwordx4 v[214:215], off
	v_lshl_add_u64 v[214:215], s[18:19], 0, v[196:197]
	s_mov_b32 m0, s31
	s_nop 0
	global_load_lds_dwordx4 v[214:215], off
	s_waitcnt vmcnt(8)
	s_waitcnt lgkmcnt(0)
	s_barrier
	s_setprio 1
	s_waitcnt lgkmcnt(0)
	v_mfma_f32_16x16x32_bf16 v[124:127], v[128:131], v[160:163], v[124:127]
	v_mfma_f32_16x16x32_bf16 v[120:123], v[136:139], v[160:163], v[120:123]
	v_mfma_f32_16x16x32_bf16 v[116:119], v[128:131], v[168:171], v[116:119]
	v_mfma_f32_16x16x32_bf16 v[112:115], v[136:139], v[168:171], v[112:115]
	v_mfma_f32_16x16x32_bf16 v[100:103], v[128:131], v[176:179], v[100:103]
	v_mfma_f32_16x16x32_bf16 v[96:99], v[136:139], v[176:179], v[96:99]
	v_mfma_f32_16x16x32_bf16 v[84:87], v[128:131], v[184:187], v[84:87]
	v_mfma_f32_16x16x32_bf16 v[80:83], v[136:139], v[184:187], v[80:83]
	v_mfma_f32_16x16x32_bf16 v[124:127], v[132:135], v[164:167], v[124:127]
	v_mfma_f32_16x16x32_bf16 v[120:123], v[140:143], v[164:167], v[120:123]
	v_mfma_f32_16x16x32_bf16 v[116:119], v[132:135], v[172:175], v[116:119]
	v_mfma_f32_16x16x32_bf16 v[112:115], v[140:143], v[172:175], v[112:115]
	v_mfma_f32_16x16x32_bf16 v[100:103], v[132:135], v[180:183], v[100:103]
	v_mfma_f32_16x16x32_bf16 v[96:99], v[140:143], v[180:183], v[96:99]
	v_mfma_f32_16x16x32_bf16 v[84:87], v[132:135], v[188:191], v[84:87]
	v_mfma_f32_16x16x32_bf16 v[80:83], v[140:143], v[188:191], v[80:83]
	s_setprio 0
	s_setprio 1
	v_mfma_f32_16x16x32_bf16 v[108:111], v[144:147], v[160:163], v[108:111]
	v_mfma_f32_16x16x32_bf16 v[104:107], v[152:155], v[160:163], v[104:107]
	v_mfma_f32_16x16x32_bf16 v[92:95], v[144:147], v[168:171], v[92:95]
	v_mfma_f32_16x16x32_bf16 v[88:91], v[152:155], v[168:171], v[88:91]
	v_mfma_f32_16x16x32_bf16 v[76:79], v[144:147], v[176:179], v[76:79]
	v_mfma_f32_16x16x32_bf16 v[72:75], v[152:155], v[176:179], v[72:75]
	v_mfma_f32_16x16x32_bf16 v[68:71], v[144:147], v[184:187], v[68:71]
	v_mfma_f32_16x16x32_bf16 v[64:67], v[152:155], v[184:187], v[64:67]
	v_mfma_f32_16x16x32_bf16 v[108:111], v[148:151], v[164:167], v[108:111]
	v_mfma_f32_16x16x32_bf16 v[104:107], v[156:159], v[164:167], v[104:107]
	v_mfma_f32_16x16x32_bf16 v[92:95], v[148:151], v[172:175], v[92:95]
	v_mfma_f32_16x16x32_bf16 v[88:91], v[156:159], v[172:175], v[88:91]
	v_mfma_f32_16x16x32_bf16 v[76:79], v[148:151], v[180:183], v[76:79]
	v_mfma_f32_16x16x32_bf16 v[72:75], v[156:159], v[180:183], v[72:75]
	v_mfma_f32_16x16x32_bf16 v[68:71], v[148:151], v[188:191], v[68:71]
	v_mfma_f32_16x16x32_bf16 v[64:67], v[156:159], v[188:191], v[64:67]
	s_setprio 0
	s_barrier
; #define PG8_STAGE(bufoff, gbase, voff) do { _Pragma("unroll") for (int _i = 0; _i < 2; ++_i) \
;         __builtin_amdgcn_global_load_lds((const unsigned*)((const char*)(gbase) + (voff)[_i]), (LAS unsigned*)(lds + (bufoff) + ldsw + _i * 8192), 16, 0, 0); } while (0)
; #define PG8_LDA(dst, b, h) do { _Pragma("unroll") for (int m = 0; m < 4; ++m) _Pragma("unroll") for (int k = 0; k < 2; ++k) dst[m][k] = *(const LAS bf16x8*)(lds + PG8_SA(b, h) + aoff + m * 2048 + k * 1024); } while (0)
; #define PG8_MMA(ai, bj, At, Bt) do { __builtin_amdgcn_s_setprio(1); _Pragma("unroll") for (int m = 0; m < 4; ++m) _Pragma("unroll") for (int n = 0; n < 2; ++n) _Pragma("unroll") for (int k = 0; k < 2; ++k) \
;         acc[ai][bj][m][n] = __builtin_amdgcn_mfma_f32_16x16x32_bf16(Bt[n][k], At[m][k], acc[ai][bj][m][n], 0, 0, 0); __builtin_amdgcn_s_setprio(0); } while (0)
; #define PG8_WAIT_V(n) asm volatile("s_waitcnt vmcnt(" #n ")" ::: "memory")
; #define PG8_WAIT_L(n) asm volatile("s_waitcnt lgkmcnt(" #n ")" ::: "memory")
; #define PG8_BAR __builtin_amdgcn_s_barrier()
; #define PG8_SCHED __builtin_amdgcn_sched_barrier(0)
; template <class Epi, int AC0, int BC0, int NT0, int AC1, int BC1, int NT1>
; __device__ __forceinline__ void gemm_phase(LAS unsigned char* lds, const Gemm g, const StaticOrder& S, const Epi& E, int tid) {
;     ...
;             PG8_LDA(At, 1, 1); PG8_STAGE(PG8_SB(1, 0), b3, voffB); PG8_STAGE(PG8_SB(1, 1), b3 + hstepB, voffB); PG8_STAGE(PG8_SA(1, 0), a3, voffA);
;             PG8_WAIT_V(8); PG8_WAIT_L(0); PG8_BAR; PG8_MMA(1, 0, At, B0); PG8_MMA(1, 1, At, B1); PG8_BAR; PG8_SCHED;
;         }
	s_add_i32 s18, s51, s27
	v_lshl_add_u64 v[206:207], v[206:207], 0, s[12:13]
	s_mov_b32 m0, s18
	ds_read_b128 v[160:163], v233 offset:49152
	ds_read_b128 v[164:167], v233 offset:50176
	ds_read_b128 v[168:171], v233 offset:51200
	ds_read_b128 v[172:175], v233 offset:52224
	ds_read_b128 v[176:179], v233 offset:53248
	ds_read_b128 v[180:183], v233 offset:54272
	ds_read_b128 v[184:187], v233 offset:55296
	ds_read_b128 v[188:191], v233 offset:56320
	global_load_lds_dwordx4 v[206:207], off
	s_add_i32 m0, s18, 0x2000
	s_add_u32 s18, s22, 0x50080
	v_lshl_add_u64 v[206:207], v[208:209], 0, s[12:13]
	s_addc_u32 s19, s23, 0
	s_add_i32 s22, s52, s27
	global_load_lds_dwordx4 v[206:207], off
	v_lshl_add_u64 v[206:207], s[18:19], 0, v[194:195]
	s_mov_b32 m0, s22
	s_nop 0
	global_load_lds_dwordx4 v[206:207], off
	v_lshl_add_u64 v[206:207], s[18:19], 0, v[198:199]
	s_add_i32 m0, s22, 0x2000
	s_nop 0
	global_load_lds_dwordx4 v[206:207], off
	v_lshl_add_u64 v[206:207], v[210:211], 0, s[12:13]
	s_mov_b32 m0, s34
	s_nop 0
	global_load_lds_dwordx4 v[206:207], off
	v_lshl_add_u64 v[206:207], v[212:213], 0, s[12:13]
	s_mov_b32 m0, s35
	s_nop 0
	global_load_lds_dwordx4 v[206:207], off
	s_waitcnt vmcnt(8)
	s_waitcnt lgkmcnt(0)
	s_barrier
	s_setprio 1
	s_waitcnt lgkmcnt(0)
	v_mfma_f32_16x16x32_bf16 v[60:63], v[128:131], v[160:163], v[60:63]
	v_mfma_f32_16x16x32_bf16 v[56:59], v[136:139], v[160:163], v[56:59]
	v_mfma_f32_16x16x32_bf16 v[52:55], v[128:131], v[168:171], v[52:55]
	v_mfma_f32_16x16x32_bf16 v[48:51], v[136:139], v[168:171], v[48:51]
	v_mfma_f32_16x16x32_bf16 v[36:39], v[128:131], v[176:179], v[36:39]
	v_mfma_f32_16x16x32_bf16 v[32:35], v[136:139], v[176:179], v[32:35]
	v_mfma_f32_16x16x32_bf16 v[20:23], v[128:131], v[184:187], v[20:23]
	v_mfma_f32_16x16x32_bf16 v[16:19], v[136:139], v[184:187], v[16:19]
	v_mfma_f32_16x16x32_bf16 v[60:63], v[132:135], v[164:167], v[60:63]
	v_mfma_f32_16x16x32_bf16 v[56:59], v[140:143], v[164:167], v[56:59]
	v_mfma_f32_16x16x32_bf16 v[52:55], v[132:135], v[172:175], v[52:55]
	v_mfma_f32_16x16x32_bf16 v[48:51], v[140:143], v[172:175], v[48:51]
	v_mfma_f32_16x16x32_bf16 v[36:39], v[132:135], v[180:183], v[36:39]
	v_mfma_f32_16x16x32_bf16 v[32:35], v[140:143], v[180:183], v[32:35]
	v_mfma_f32_16x16x32_bf16 v[20:23], v[132:135], v[188:191], v[20:23]
	v_mfma_f32_16x16x32_bf16 v[16:19], v[140:143], v[188:191], v[16:19]
	s_setprio 0
	s_setprio 1
	v_mfma_f32_16x16x32_bf16 v[44:47], v[144:147], v[160:163], v[44:47]
	v_mfma_f32_16x16x32_bf16 v[40:43], v[152:155], v[160:163], v[40:43]
	v_mfma_f32_16x16x32_bf16 v[28:31], v[144:147], v[168:171], v[28:31]
	v_mfma_f32_16x16x32_bf16 v[24:27], v[152:155], v[168:171], v[24:27]
	v_mfma_f32_16x16x32_bf16 v[12:15], v[144:147], v[176:179], v[12:15]
	v_mfma_f32_16x16x32_bf16 v[8:11], v[152:155], v[176:179], v[8:11]
	v_mfma_f32_16x16x32_bf16 v[4:7], v[144:147], v[184:187], v[4:7]
	v_mfma_f32_16x16x32_bf16 v[0:3], v[152:155], v[184:187], v[0:3]
	v_mfma_f32_16x16x32_bf16 v[44:47], v[148:151], v[164:167], v[44:47]
	v_mfma_f32_16x16x32_bf16 v[40:43], v[156:159], v[164:167], v[40:43]
	v_mfma_f32_16x16x32_bf16 v[28:31], v[148:151], v[172:175], v[28:31]
	v_mfma_f32_16x16x32_bf16 v[24:27], v[156:159], v[172:175], v[24:27]
	v_mfma_f32_16x16x32_bf16 v[12:15], v[148:151], v[180:183], v[12:15]
	v_mfma_f32_16x16x32_bf16 v[8:11], v[156:159], v[180:183], v[8:11]
	v_mfma_f32_16x16x32_bf16 v[4:7], v[148:151], v[188:191], v[4:7]
	v_mfma_f32_16x16x32_bf16 v[0:3], v[156:159], v[188:191], v[0:3]
	s_add_i32 s50, s50, 2
	s_add_u32 s46, s46, 0x100
	s_addc_u32 s47, s47, 0
	s_cmp_gt_i32 s50, s33
	s_mov_b64 s[18:19], s[20:21]
	s_setprio 0
	s_barrier
	s_cbranch_scc0 .LBB0_992
	s_and_b64 vcc, exec, s[10:11]
	s_cbranch_vccz .LBB0_995
	s_barrier
